# v32 with the P2/P3 first/last split keyed on permuted-id bit 3
# speedup vs baseline: 1.0085x; 1.0085x over previous
; #define LAS __attribute__((address_space(3)))
; DI float bf2f(unsigned short u) { return __uint_as_float(((unsigned)u) << 16); }
; DI float gamma_of(int h) { return 1.0f - exp2f(-5.0f - (float)h); }
; DI void ret_decode_unit(LAS unsigned char* lds, const bf16_t* Z, const float* S0, float* S1, bf16_t* MIX, const float* rng, int b, int h, int tid) {
;     LAS float* qv = (LAS float*)lds; LAS float* red = qv + 768;
;     const int lane = tid & 63, wid = tid >> 6;
;     const bf16_t* zrow = Z + (size_t)(LP + b) * INW;
;     if (tid < 256) { qv[tid] = bf2f(zrow[C_RQ + h * 256 + tid]); qv[256 + tid] = bf2f(zrow[C_RK + h * 256 + tid]); qv[512 + tid] = bf2f(zrow[C_RV + h * 256 + tid]); }
;     __syncthreads();
;     const float gm = gamma_of(h);
;     const f32x4 v4 = *(const LAS f32x4*)(qv + 512 + 4 * lane);
;     f32x4 acc = {0.f, 0.f, 0.f, 0.f};
;     const size_t off = ((size_t)(b * 4 + h) * 256 + wid * 32) * 256 + 4 * lane;
;     const float* s0 = S0 + off; float* s1 = S1 + off;
; __global__ void __launch_bounds__(512, 2) fwd_kernel(Args a) {
;     ...
;     if (IN(2)) for (int rep_ = 0; rep_ < 1 + ((DUPMASK >> 2) & 1); ++rep_) { if (rep_) xcd_barrier(bar);
;         if (bx & 1) for (int u = bx; u < 256; u += G) ret_decode_unit(lds, Z, state0, out + O_SS, MIX, rng, u >> 2, u & 3, tid);
;         for (int u = bx; u < 256; u += G) ret_step1(lds, Z, KV, u >> 2, u & 3, tid);
;         if (!(bx & 1)) for (int u = bx; u < 256; u += G) ret_decode_unit(lds, Z, state0, out + O_SS, MIX, rng, u >> 2, u & 3, tid);
;     }
.LBB0_226:
	s_and_b32 s98, s92, 7
	s_lshl_b32 s98, s98, 5
	s_lshr_b32 s99, s92, 3
	s_or_b32 s92, s98, s99
	s_cmp_lt_i32 s62, 3
	s_cselect_b64 s[2:3], -1, 0
	s_add_u32 s56, s60, 0x8000000
	s_addc_u32 s57, s61, 0
	s_add_u32 s4, s60, 0xfc00000
	s_addc_u32 s5, s61, 0
	v_writelane_b32 v254, s4, 23
	s_and_b64 s[10:11], s[2:3], s[0:1]
	s_andn2_b64 vcc, exec, s[10:11]
	v_writelane_b32 v254, s5, 24
	v_lshrrev_b32_e32 v252, 6, v253
	v_cmp_gt_u32_e64 s[0:1], 64, v253
	s_cbranch_vccnz .LBB0_250
	s_bitcmp0_b32 s92, 3
	v_readlane_b32 s68, v254, 7
	s_cselect_b64 s[14:15], -1, 0
	s_cmpk_gt_i32 s92, 0xff
	v_readlane_b32 s82, v254, 21
	v_lshlrev_b32_e32 v0, 2, v253
	s_cselect_b64 s[2:3], -1, 0
	v_readlane_b32 s83, v254, 22
	s_add_u32 s12, s82, 0x5220000
	v_and_b32_e32 v147, 0xfc, v0
	v_readlane_b32 s72, v254, 11
	v_readlane_b32 s73, v254, 12
	s_addc_u32 s13, s83, 0
	s_movk_i32 s4, 0x100
	v_add_u32_e32 v146, 0, v0
	v_lshlrev_b32_e32 v20, 2, v147
	v_mov_b32_e32 v21, 0
	v_lshl_add_u32 v149, v252, 7, 0
	v_mul_u32_u24_e32 v0, 0x380, v252
	s_or_b64 s[2:3], s[14:15], s[2:3]
	s_mov_b32 s17, 0
	v_add_u32_e32 v144, 0x900, v253
	v_add_u32_e32 v145, 0xd00, v253
	v_cmp_gt_u32_e64 s[6:7], s4, v253
	v_add_u32_e32 v148, 0, v20
	v_lshl_or_b32 v128, v252, 13, v147
	v_mov_b32_e32 v129, v21
	v_add3_u32 v150, v149, v0, v20
	v_lshl_add_u64 v[130:131], s[72:73], 0, v[20:21]
	s_and_b64 vcc, exec, s[2:3]
	v_readlane_b32 s69, v254, 8
	v_readlane_b32 s70, v254, 9
	v_readlane_b32 s71, v254, 10
	v_readlane_b32 s74, v254, 13
	v_readlane_b32 s75, v254, 14
	v_readlane_b32 s76, v254, 15
	v_readlane_b32 s77, v254, 16
	v_readlane_b32 s78, v254, 17
	v_readlane_b32 s79, v254, 18
	v_readlane_b32 s80, v254, 19
	v_readlane_b32 s81, v254, 20
	s_cbranch_vccnz .LBB0_236
	v_mbcnt_lo_u32_b32 v0, -1, 0
	v_mov_b32_e32 v30, 0x42800000
	v_mov_b32_e32 v31, 0x358637bd
	v_mbcnt_hi_u32_b32 v32, -1, v0
	s_mov_b32 s18, s92
	s_branch .LBB0_230
